# entry cooperative-groups grid sync removed (first XCD barrier self-synchronises)
# speedup vs baseline: 1.0091x; 1.0091x over previous
.LBB0_7:
	s_or_b64 exec, exec, s[0:1]
.LBB0_19:
	v_writelane_b32 v252, s14, 5
	s_nop 1
	v_writelane_b32 v252, s15, 6
	s_nop 0
	v_readlane_b32 s0, v252, 3
	v_readlane_b32 s1, v252, 4
	s_cmp_le_i32 s1, s0
	s_cbranch_scc0 .LBB0_20
	s_getpc_b64 s[98:99]
